# combined: paired V^T dword writes + redundant barrier between attention and pool removed + PA rstd-table reduction behind prologue DMA
# speedup vs baseline: 1.0100x; 1.0040x over previous
; __device__ __forceinline__ void pool_tokens8(const bf16* PROJ, bf16* DA, int t0, int lane) {
;     const int sf = t0 & (SEQ - 1), g = lane >> 4, half = 1 << g;
;     const bf16* zp = PROJ + (size_t)t0 * INW + lane * 8;
;     v4u row[23];
; #pragma unroll
;     for (int ri = 0; ri < 23; ++ri) {
;         const int off = ri - 8, sp = sf + off;
;         row[ri] = (v4u){0u, 0u, 0u, 0u};
;         if ((off >= -half) && (off < 7 + half) && (sp >= 0) && (sp < SEQ)) row[ri] = *(const v4u*)(zp + (ptrdiff_t)off * INW);
.LBB0_392:
	v_readlane_b32 s6, v239, 14
	v_lshlrev_b32_e32 v2, 4, v67
	v_mov_b32_e32 v3, v66
	v_readlane_b32 s7, v239, 15
	v_lshrrev_b32_e32 v99, 4, v67
	v_cmp_eq_u32_e64 s[36:37], 3, v99
	v_lshl_add_u64 v[96:97], s[6:7], 0, v[2:3]
	v_readlane_b32 s6, v239, 16
	v_readlane_b32 s7, v239, 17
	s_and_b64 s[38:39], s[36:37], s[6:7]
	v_mov_b32_e32 v72, 0
	v_mov_b32_e32 v84, 0
	v_mov_b32_e32 v85, 0
	v_mov_b32_e32 v86, 0
	v_mov_b32_e32 v87, 0
	s_and_saveexec_b64 s[40:41], s[38:39]
	s_cbranch_execz .LBB0_394
	v_add_co_u32_e32 v2, vcc, 0xffff3000, v96
	s_nop 1
	v_addc_co_u32_e32 v3, vcc, -1, v97, vcc
	global_load_dwordx4 v[84:87], v[2:3], off
